# combo4 + attention main loop: dropped m0 save/restore around LDS-DMA, merged redundant max canonicalisation, removed add of zero
# baseline (speedup 1.0000x reference)
.LBB0_198:
	v_add_u32_e32 v0, s8, v206
	ds_read_b64_tr_b16 v[178:179], v0 offset:24576
	ds_read_b64_tr_b16 v[180:181], v0 offset:25088
	s_waitcnt lgkmcnt(9)
	v_mfma_f32_32x32x16_bf16 v[98:113], v[174:177], v[138:141], v[34:49]
	v_add_f32_e32 v82, v66, v67
	v_add_f32_e32 v82, v68, v82
	v_add_f32_e32 v82, v69, v82
	v_add_f32_e32 v82, v70, v82
	v_add_f32_e32 v82, v71, v82
	v_cvt_pk_bf16_f32 v142, v66, v67
	v_cvt_pk_bf16_f32 v143, v68, v69
	ds_read_b64_tr_b16 v[174:175], v0 offset:28672
	ds_read_b64_tr_b16 v[176:177], v0 offset:29184
	v_add_f32_e32 v66, v72, v82
	s_waitcnt lgkmcnt(10)
	v_mfma_f32_32x32x16_bf16 v[82:97], v[170:173], v[138:141], v[34:49]
	v_add_f32_e32 v66, v73, v66
	v_add_f32_e32 v66, v74, v66
	v_add_f32_e32 v122, v75, v66
	v_cvt_pk_bf16_f32 v144, v70, v71
	v_cvt_pk_bf16_f32 v145, v72, v73
	ds_read_b64_tr_b16 v[66:67], v0 offset:25600
	ds_read_b64_tr_b16 v[68:69], v0 offset:26112
	s_waitcnt lgkmcnt(11)
	v_mfma_f32_32x32x16_bf16 v[98:113], v[166:169], v[126:129], v[98:113]
	v_add_f32_e32 v70, v76, v122
	v_add_f32_e32 v70, v77, v70
	v_add_f32_e32 v70, v78, v70
	v_add_f32_e32 v122, v79, v70
	v_cvt_pk_bf16_f32 v134, v74, v75
	v_cvt_pk_bf16_f32 v135, v76, v77
	ds_read_b64_tr_b16 v[70:71], v0 offset:29696
	ds_read_b64_tr_b16 v[72:73], v0 offset:30208
	s_waitcnt lgkmcnt(12)
	v_mfma_f32_32x32x16_bf16 v[82:97], v[162:165], v[126:129], v[82:97]
	v_add_f32_e32 v74, v80, v122
	v_add_f32_e32 v74, v81, v74
	v_add_f32_e32 v74, v50, v74
	v_add_f32_e32 v122, v51, v74
	v_cvt_pk_bf16_f32 v136, v78, v79
	v_cvt_pk_bf16_f32 v137, v80, v81
	ds_read_b64_tr_b16 v[74:75], v0 offset:26624
	ds_read_b64_tr_b16 v[76:77], v0 offset:27136
	s_waitcnt lgkmcnt(13)
	v_mfma_f32_32x32x16_bf16 v[98:113], v[158:161], v[118:121], v[98:113]
	v_add_f32_e32 v78, v52, v122
	v_add_f32_e32 v78, v53, v78
	v_add_f32_e32 v78, v54, v78
	v_add_f32_e32 v78, v55, v78
	v_cvt_pk_bf16_f32 v130, v50, v51
	v_cvt_pk_bf16_f32 v131, v52, v53
	ds_read_b64_tr_b16 v[50:51], v0 offset:30720
	ds_read_b64_tr_b16 v[52:53], v0 offset:31232
	s_waitcnt lgkmcnt(14)
	v_mfma_f32_32x32x16_bf16 v[82:97], v[154:157], v[118:121], v[82:97]
	v_add_f32_e32 v78, v56, v78
	v_add_f32_e32 v78, v57, v78
	v_add_f32_e32 v78, v58, v78
	v_add_f32_e32 v78, v59, v78
	v_cvt_pk_bf16_f32 v132, v54, v55
	v_cvt_pk_bf16_f32 v133, v56, v57
	ds_read_b64_tr_b16 v[54:55], v0 offset:27648
	ds_read_b64_tr_b16 v[56:57], v0 offset:28160
	s_waitcnt lgkmcnt(14)
	v_mfma_f32_32x32x16_bf16 v[98:113], v[150:153], v[114:117], v[98:113]
	v_add_f32_e32 v78, v60, v78
	v_add_f32_e32 v78, v61, v78
	v_add_f32_e32 v78, v62, v78
	v_add_f32_e32 v78, v63, v78
	v_cvt_pk_bf16_f32 v122, v58, v59
	v_cvt_pk_bf16_f32 v123, v60, v61
	ds_read_b64_tr_b16 v[58:59], v0 offset:31744
	ds_read_b64_tr_b16 v[60:61], v0 offset:32256
	v_mfma_f32_32x32x16_bf16 v[82:97], v[146:149], v[114:117], v[82:97]
	v_add_f32_e32 v0, v64, v78
	v_add_f32_e32 v0, v65, v0
	v_cvt_pk_bf16_f32 v124, v62, v63
	v_cvt_pk_bf16_f32 v125, v64, v65
	v_lshl_add_u64 v[62:63], v[184:185], 0, s[98:99]
	s_add_i32 s8, s21, s40
	s_mov_b32 m0, s8
	s_nop 0
	global_load_lds_dwordx4 v[62:63], off
	v_lshl_add_u64 v[62:63], v[182:183], 0, s[98:99]
	s_add_i32 s8, s18, s41
	s_mov_b32 m0, s8
	s_nop 0
	global_load_lds_dwordx4 v[62:63], off
	v_max_f32_e32 v62, v98, v99
	v_max3_f32 v63, v100, v101, v83
	v_max3_f32 v62, v62, v82, v84
	v_max3_f32 v62, v62, v85, v102
	v_max3_f32 v63, v63, v104, v105
	v_max3_f32 v62, v62, v103, v86
	v_max3_f32 v63, v63, v88, v89
	v_max3_f32 v62, v62, v87, v106
	v_max3_f32 v63, v63, v108, v109
	v_max3_f32 v62, v62, v107, v90
	v_max3_f32 v63, v63, v92, v93
	v_max3_f32 v62, v62, v91, v110
	v_max3_f32 v63, v63, v112, v113
	v_max3_f32 v62, v62, v111, v94
	v_max3_f32 v63, v63, v96, v97
	v_max3_f32 v62, v62, v95, v63
	v_mov_b32_e32 v63, v62
	s_nop 1
	v_permlane32_swap_b32_e32 v62, v63
	v_max_f32_e32 v63, v63, v63
	v_max_f32_e32 v62, v62, v62
	v_max_f32_e32 v62, v62, v63
	v_cmp_lt_f32_e32 vcc, s91, v62
	s_cmp_lg_u64 vcc, 0
	v_add_f32_e32 v0, v208, v0
	s_cselect_b64 s[8:9], -1, 0
	s_cbranch_vccnz .LBB0_206

.LBB0_201:
	s_add_i32 s8, s18, 0x2000
	s_cmpk_lg_i32 s18, 0x4000
	s_cselect_b32 s44, s8, 0
	v_add_u32_e32 v186, s21, v206
	ds_read_b64_tr_b16 v[150:151], v186 offset:24576
	ds_read_b64_tr_b16 v[152:153], v186 offset:25088
	s_waitcnt lgkmcnt(9)
	v_mfma_f32_32x32x16_bf16 v[66:81], v[62:65], v[138:141], v[34:49]
	v_add_f32_e32 v50, v98, v99
	v_add_f32_e32 v50, v100, v50
	v_add_f32_e32 v50, v101, v50
	v_add_f32_e32 v50, v102, v50
	v_add_f32_e32 v50, v103, v50
	v_cvt_pk_bf16_f32 v142, v98, v99
	v_cvt_pk_bf16_f32 v143, v100, v101
	ds_read_b64_tr_b16 v[146:147], v186 offset:28672
	ds_read_b64_tr_b16 v[148:149], v186 offset:29184
	v_add_f32_e32 v50, v104, v50
	v_add_f32_e32 v50, v105, v50
	v_add_f32_e32 v50, v106, v50
	v_add_f32_e32 v122, v107, v50
	s_waitcnt lgkmcnt(10)
	v_mfma_f32_32x32x16_bf16 v[50:65], v[174:177], v[138:141], v[34:49]
	v_cvt_pk_bf16_f32 v144, v102, v103
	v_cvt_pk_bf16_f32 v145, v104, v105
	ds_read_b64_tr_b16 v[98:99], v186 offset:25600
	ds_read_b64_tr_b16 v[100:101], v186 offset:26112
	s_waitcnt lgkmcnt(11)
	v_mfma_f32_32x32x16_bf16 v[66:81], v[178:181], v[126:129], v[66:81]
	v_add_f32_e32 v102, v108, v122
	v_add_f32_e32 v102, v109, v102
	v_add_f32_e32 v102, v110, v102
	v_add_f32_e32 v122, v111, v102
	v_cvt_pk_bf16_f32 v134, v106, v107
	v_cvt_pk_bf16_f32 v135, v108, v109
	ds_read_b64_tr_b16 v[102:103], v186 offset:29696
	ds_read_b64_tr_b16 v[104:105], v186 offset:30208
	s_waitcnt lgkmcnt(12)
	v_mfma_f32_32x32x16_bf16 v[50:65], v[170:173], v[126:129], v[50:65]
	v_add_f32_e32 v106, v112, v122
	v_add_f32_e32 v106, v113, v106
	v_add_f32_e32 v106, v82, v106
	v_add_f32_e32 v122, v83, v106
	v_cvt_pk_bf16_f32 v136, v110, v111
	v_cvt_pk_bf16_f32 v137, v112, v113
	ds_read_b64_tr_b16 v[106:107], v186 offset:26624
	ds_read_b64_tr_b16 v[108:109], v186 offset:27136
	s_waitcnt lgkmcnt(13)
	v_mfma_f32_32x32x16_bf16 v[66:81], v[166:169], v[118:121], v[66:81]
	v_add_f32_e32 v110, v84, v122
	v_add_f32_e32 v110, v85, v110
	v_add_f32_e32 v110, v86, v110
	v_add_f32_e32 v110, v87, v110
	v_cvt_pk_bf16_f32 v130, v82, v83
	v_cvt_pk_bf16_f32 v131, v84, v85
	ds_read_b64_tr_b16 v[82:83], v186 offset:30720
	ds_read_b64_tr_b16 v[84:85], v186 offset:31232
	s_waitcnt lgkmcnt(14)
	v_mfma_f32_32x32x16_bf16 v[50:65], v[162:165], v[118:121], v[50:65]
	v_add_f32_e32 v110, v88, v110
	v_add_f32_e32 v110, v89, v110
	v_add_f32_e32 v110, v90, v110
	v_add_f32_e32 v110, v91, v110
	v_cvt_pk_bf16_f32 v132, v86, v87
	v_cvt_pk_bf16_f32 v133, v88, v89
	ds_read_b64_tr_b16 v[86:87], v186 offset:27648
	ds_read_b64_tr_b16 v[88:89], v186 offset:28160
	s_waitcnt lgkmcnt(14)
	v_mfma_f32_32x32x16_bf16 v[66:81], v[158:161], v[114:117], v[66:81]
	v_add_f32_e32 v110, v92, v110
	v_add_f32_e32 v110, v93, v110
	v_add_f32_e32 v110, v94, v110
	v_add_f32_e32 v110, v95, v110
	v_cvt_pk_bf16_f32 v122, v90, v91
	v_cvt_pk_bf16_f32 v123, v92, v93
	ds_read_b64_tr_b16 v[90:91], v186 offset:31744
	ds_read_b64_tr_b16 v[92:93], v186 offset:32256
	v_mfma_f32_32x32x16_bf16 v[50:65], v[154:157], v[114:117], v[50:65]
	v_add_f32_e32 v110, v96, v110
	v_add_f32_e32 v110, v97, v110
	v_add_f32_e32 v110, 0, v110
	v_cvt_pk_bf16_f32 v124, v94, v95
	v_cvt_pk_bf16_f32 v125, v96, v97
	v_max_f32_e32 v94, v67, v67
	v_max_f32_e32 v95, v66, v66
	v_max_f32_e32 v94, v95, v94
	s_nop 3
	v_max3_f32 v95, v68, v69, v51
	v_max3_f32 v94, v94, v50, v52
	v_max3_f32 v94, v94, v53, v70
	v_max3_f32 v95, v95, v72, v73
	v_max3_f32 v94, v94, v71, v54
	v_max3_f32 v95, v95, v56, v57
	v_max3_f32 v94, v94, v55, v74
	v_max3_f32 v95, v95, v76, v77
	v_max3_f32 v94, v94, v75, v58
	v_max3_f32 v95, v95, v60, v61
	v_max3_f32 v94, v94, v59, v78
	v_max3_f32 v95, v95, v80, v81
	v_max3_f32 v94, v94, v79, v62
	v_max3_f32 v95, v95, v64, v65
	v_add_f32_e32 v208, v0, v110
	v_max3_f32 v0, v94, v63, v95
	v_mov_b32_e32 v94, v0
	s_nop 1
	v_permlane32_swap_b32_e32 v0, v94
	v_max_f32_e32 v94, v94, v94
	v_max_f32_e32 v0, v0, v0
	s_add_i32 s8, s18, s40
	s_mov_b32 m0, s8
	s_nop 0
	global_load_lds_dwordx4 v[184:185], off
	v_max_f32_e32 v0, v0, v94
	s_add_i32 s8, s44, s41
	s_mov_b32 m0, s8
	s_nop 0
	global_load_lds_dwordx4 v[182:183], off
	v_cmp_lt_f32_e32 vcc, s91, v0
	s_cmp_lg_u64 vcc, 0
	s_cselect_b64 s[8:9], -1, 0
	s_cbranch_vccnz .LBB0_209
